# MoBA unit routing prologue: 19 of 24 kmean/q loads issued up front into dead registers (5 late loads right after their quad frees), per-MFMA vmcnt recomputed
# baseline (speedup 1.0000x reference)
.LBB0_877:
	s_and_b32 s10, s58, 56
	s_or_b32 s59, s10, s16
	s_and_b32 s56, s58, 7
	s_xor_b32 s61, s56, 15
	s_lshl_b32 s57, s59, 12
	s_lshl_b32 s60, s61, 8
	v_lshl_or_b32 v2, v154, 1, s57
	s_or_b32 s10, s57, s60
	v_lshl_add_u64 v[148:149], v[156:157], 0, v[2:3]
	s_add_u32 s10, s10, s3
	s_addc_u32 s11, 0, s33
	s_lshl_b64 s[10:11], s[10:11], 8
	v_lshl_add_u64 v[36:37], v[152:153], 0, s[10:11]
	v_lshl_add_u64 v[172:173], v[158:159], 0, v[2:3]
	global_load_dwordx4 v[4:7], v[148:149], off
	global_load_dwordx4 v[100:103], v[36:37], off
	global_load_dwordx4 v[8:11], v[172:173], off
	global_load_dwordx4 v[12:15], v[148:149], off offset:32
	global_load_dwordx4 v[104:107], v[36:37], off offset:32
	global_load_dwordx4 v[16:19], v[172:173], off offset:32
	global_load_dwordx4 v[46:49], v[148:149], off offset:64
	global_load_dwordx4 v[108:111], v[36:37], off offset:64
	global_load_dwordx4 v[50:53], v[172:173], off offset:64
	global_load_dwordx4 v[54:57], v[148:149], off offset:96
	global_load_dwordx4 v[112:115], v[36:37], off offset:96
	global_load_dwordx4 v[58:61], v[172:173], off offset:96
	global_load_dwordx4 v[62:65], v[148:149], off offset:128
	global_load_dwordx4 v[116:119], v[36:37], off offset:128
	global_load_dwordx4 v[120:123], v[36:37], off offset:160
	global_load_dwordx4 v[124:127], v[36:37], off offset:192
	global_load_dwordx4 v[128:131], v[36:37], off offset:224
	global_load_dwordx4 v[38:41], v[148:149], off offset:224
	global_load_dwordx4 v[42:45], v[172:173], off offset:224
	s_mov_b32 s16, 0
	s_mov_b32 s17, s16
	s_mov_b32 s18, s16
	s_mov_b32 s19, s16
	s_mov_b32 s20, s16
	s_mov_b32 s21, s16
	s_mov_b32 s22, s16
	s_mov_b32 s23, s16
	s_mov_b32 s24, s16
	s_mov_b32 s25, s16
	s_mov_b32 s26, s16
	s_mov_b32 s27, s16
	s_mov_b32 s28, s16
	s_mov_b32 s29, s16
	s_mov_b32 s30, s16
	s_mov_b32 s31, s16
	s_lshl_b32 s44, s59, 20
	v_lshl_add_u64 v[174:175], v[164:165], 0, s[44:45]
	v_lshlrev_b32_e32 v176, 1, v162
	v_mov_b32_e32 v177, v3
	v_lshlrev_b32_e32 v178, 1, v166
	v_mov_b32_e32 v179, v3
	v_add_u32_e32 v211, 0x4400, v209
	v_add_u32_e32 v212, 0x4410, v209
	v_lshl_add_u64 v[170:171], v[174:175], 0, v[178:179]
	s_waitcnt vmcnt(17)
	v_mfma_f32_32x32x16_bf16 v[20:35], v[4:7], v[100:103], 0
	global_load_dwordx4 v[4:7], v[172:173], off offset:128
	s_waitcnt vmcnt(17)
	v_mfma_f32_32x32x16_bf16 v[20:35], v[8:11], v[100:103], v[20:35]
	global_load_dwordx4 v[8:11], v[148:149], off offset:160
	s_waitcnt vmcnt(16)
	v_mfma_f32_32x32x16_bf16 v[20:35], v[12:15], v[104:107], v[20:35]
	global_load_dwordx4 v[12:15], v[172:173], off offset:160
	s_waitcnt vmcnt(16)
	v_mfma_f32_32x32x16_bf16 v[20:35], v[16:19], v[104:107], v[20:35]
	global_load_dwordx4 v[16:19], v[148:149], off offset:192
	s_waitcnt vmcnt(15)
	v_mfma_f32_32x32x16_bf16 v[20:35], v[46:49], v[108:111], v[20:35]
	global_load_dwordx4 v[46:49], v[172:173], off offset:192
	s_waitcnt vmcnt(15)
	v_mfma_f32_32x32x16_bf16 v[20:35], v[50:53], v[108:111], v[20:35]
	s_waitcnt vmcnt(13)
	v_mfma_f32_32x32x16_bf16 v[20:35], v[54:57], v[112:115], v[20:35]
	s_waitcnt vmcnt(12)
	v_mfma_f32_32x32x16_bf16 v[20:35], v[58:61], v[112:115], v[20:35]
	s_waitcnt vmcnt(10)
	v_mfma_f32_32x32x16_bf16 v[20:35], v[62:65], v[116:119], v[20:35]
	s_waitcnt vmcnt(4)
	v_mfma_f32_32x32x16_bf16 v[20:35], v[4:7], v[116:119], v[20:35]
	v_add_u32_e32 v36, s60, v201
	v_ashrrev_i32_e32 v37, 31, v36
	s_barrier
	s_waitcnt vmcnt(3)
	v_mfma_f32_32x32x16_bf16 v[20:35], v[8:11], v[120:123], v[20:35]
	s_waitcnt vmcnt(2)
	v_mfma_f32_32x32x16_bf16 v[20:35], v[12:15], v[120:123], v[20:35]
	s_waitcnt vmcnt(1)
	v_mfma_f32_32x32x16_bf16 v[20:35], v[16:19], v[124:127], v[20:35]
	s_waitcnt vmcnt(0)
	v_mfma_f32_32x32x16_bf16 v[20:35], v[46:49], v[124:127], v[20:35]
	v_mov_b64_e32 v[4:5], s[16:17]
	v_mov_b64_e32 v[6:7], s[18:19]
	v_mov_b64_e32 v[8:9], s[20:21]
	v_mov_b64_e32 v[10:11], s[22:23]
	v_mov_b64_e32 v[12:13], s[24:25]
	v_mov_b64_e32 v[14:15], s[26:27]
	v_mov_b64_e32 v[16:17], s[28:29]
	s_waitcnt vmcnt(6)
	v_mfma_f32_32x32x16_bf16 v[20:35], v[38:41], v[128:131], v[20:35]
	v_mov_b64_e32 v[18:19], s[30:31]
	s_add_u32 s18, s34, s44
	s_addc_u32 s19, s35, 0
	s_sub_i32 s10, 11, s56
	s_lshl_b32 s44, s61, 9
	s_lshl_b32 s17, s61, 2
	v_lshl_add_u64 v[168:169], s[18:19], 0, v[176:177]
	s_waitcnt vmcnt(5)
	v_mfma_f32_32x32x16_bf16 v[20:35], v[42:45], v[128:131], v[20:35]
	s_or_b32 s28, s17, 2
	s_or_b32 s29, s60, 64
	s_nop 9
	v_cmp_lt_i32_e32 vcc, -1, v20
	v_mov_b32_e32 v2, v20
	v_mov_b32_e32 v28, v20
	v_cndmask_b32_e32 v29, -1, v207, vcc
	v_cmp_lt_i32_e32 vcc, -1, v21
	v_mov_b32_e32 v30, v21
	v_mov_b32_e32 v31, v21
	v_cndmask_b32_e32 v32, -1, v207, vcc
	v_cmp_lt_i32_e32 vcc, -1, v22
	v_permlane32_swap_b32_e32 v2, v28
	s_nop 0
	v_cndmask_b32_e32 v35, -1, v207, vcc
	v_cmp_lt_i32_e32 vcc, -1, v23
	v_mov_b32_e32 v33, v22
	v_mov_b32_e32 v34, v22
	v_cndmask_b32_e32 v40, -1, v207, vcc
	v_cmp_lt_i32_e32 vcc, -1, v24
	v_xor_b32_e32 v20, v29, v20
	v_permlane32_swap_b32_e32 v30, v31
	v_cndmask_b32_e32 v43, -1, v207, vcc
	v_cmp_lt_i32_e32 vcc, -1, v25
	v_cndmask_b32_e64 v2, v2, v28, s[40:41]
	v_mov_b32_e32 v38, v23
	v_cndmask_b32_e32 v46, -1, v207, vcc
	v_cmp_lt_i32_e32 vcc, -1, v26
	v_mov_b32_e32 v39, v23
	v_xor_b32_e32 v21, v32, v21
	v_cndmask_b32_e32 v49, -1, v207, vcc
	v_cmp_lt_i32_e32 vcc, -1, v27
	v_permlane32_swap_b32_e32 v33, v34
	s_nop 0
	v_cndmask_b32_e32 v52, -1, v207, vcc
	v_and_or_b32 v28, v20, -16, v167
	v_cndmask_b32_e64 v20, v30, v31, s[40:41]
	v_cmp_lt_i32_e32 vcc, -1, v2
	v_mov_b32_e32 v41, v24
	v_mov_b32_e32 v42, v24
	v_xor_b32_e32 v22, v35, v22
	v_permlane32_swap_b32_e32 v38, v39
	v_and_or_b32 v29, v21, -16, v183
	v_cndmask_b32_e64 v21, v33, v34, s[40:41]
	v_cndmask_b32_e32 v35, -1, v207, vcc
	v_cmp_lt_i32_e32 vcc, -1, v20
	v_xor_b32_e32 v23, v40, v23
	v_permlane32_swap_b32_e32 v41, v42
	v_and_or_b32 v30, v22, -16, v188
	v_cndmask_b32_e64 v22, v38, v39, s[40:41]
	v_cndmask_b32_e32 v38, -1, v207, vcc
	v_cmp_lt_i32_e32 vcc, -1, v21
	v_mov_b32_e32 v44, v25
	v_mov_b32_e32 v45, v25
	v_and_or_b32 v31, v23, -16, v192
	v_cndmask_b32_e64 v23, v41, v42, s[40:41]
	v_cndmask_b32_e32 v39, -1, v207, vcc
	v_cmp_lt_i32_e32 vcc, -1, v22
	v_bitop3_b32 v24, v43, -16, v24 bitop3:0x48
	v_permlane32_swap_b32_e32 v44, v45
	v_cndmask_b32_e32 v40, -1, v207, vcc
	v_cmp_lt_i32_e32 vcc, -1, v23
	v_mov_b32_e32 v47, v26
	v_mov_b32_e32 v48, v26
	v_bitop3_b32 v24, v160, 7, v24 bitop3:0x36
	v_cndmask_b32_e64 v32, v44, v45, s[40:41]
	v_cndmask_b32_e32 v41, -1, v207, vcc
	v_cmp_gt_u32_e32 vcc, s61, v193
	v_xor_b32_e32 v25, v46, v25
	v_permlane32_swap_b32_e32 v47, v48
	v_cndmask_b32_e32 v24, 0, v24, vcc
	v_cmp_lt_i32_e32 vcc, -1, v32
	v_mov_b32_e32 v50, v27
	v_mov_b32_e32 v51, v27
	v_and_or_b32 v25, v25, -16, v196
	v_cndmask_b32_e64 v33, v47, v48, s[40:41]
	v_cndmask_b32_e32 v42, -1, v207, vcc
	v_cmp_gt_u32_e32 vcc, s61, v189
	v_xor_b32_e32 v26, v49, v26
	v_permlane32_swap_b32_e32 v50, v51
	v_cndmask_b32_e32 v25, 0, v25, vcc
	v_cmp_lt_i32_e32 vcc, -1, v33
	v_and_or_b32 v26, v26, -16, v198
	v_cndmask_b32_e64 v34, v50, v51, s[40:41]
	v_cndmask_b32_e32 v43, -1, v207, vcc
	v_cmp_gt_u32_e32 vcc, s61, v184
	v_xor_b32_e32 v27, v52, v27
	v_and_or_b32 v27, v27, -16, v199
	v_cndmask_b32_e32 v26, 0, v26, vcc
	v_cmp_lt_i32_e32 vcc, -1, v34
	v_xor_b32_e32 v20, v38, v20
	v_xor_b32_e32 v21, v39, v21
	v_cndmask_b32_e32 v44, -1, v207, vcc
	v_cmp_gt_u32_e32 vcc, s61, v180
	v_xor_b32_e32 v23, v41, v23
	v_xor_b32_e32 v2, v35, v2
	v_cndmask_b32_e32 v27, 0, v27, vcc
	v_xor_b32_e32 v22, v40, v22
	v_xor_b32_e32 v32, v42, v32
	v_and_or_b32 v39, v20, -16, v184
	v_and_or_b32 v20, v21, -16, v189
	v_and_or_b32 v21, v23, -16, v190
	v_cmp_gt_u32_e32 vcc, s10, v194
	v_max3_u32 v45, v28, v29, v30
	v_xor_b32_e32 v33, v43, v33
	v_and_or_b32 v38, v2, -16, v180
	v_and_or_b32 v2, v22, -16, v193
	v_and_or_b32 v22, v32, -16, v185
	v_cndmask_b32_e32 v21, 0, v21, vcc
	v_cmp_gt_u32_e32 vcc, s10, v195
	v_xor_b32_e32 v34, v44, v34
	v_max3_u32 v35, v45, v31, v24
	v_and_or_b32 v23, v33, -16, v181
	v_cndmask_b32_e32 v22, 0, v22, vcc
	v_cmp_gt_u32_e32 vcc, s10, v197
	v_and_or_b32 v32, v34, -16, v160
	v_max3_u32 v33, v35, v25, v26
	v_cndmask_b32_e32 v23, 0, v23, vcc
	v_cmp_lt_u32_e32 vcc, s56, v160
	s_nop 1
	v_cndmask_b32_e32 v40, 0, v32, vcc
	v_max3_u32 v32, v33, v27, v38
	v_max3_u32 v32, v32, v39, v20
	v_max3_u32 v32, v32, v2, v21
	v_max3_u32 v41, v32, v22, v23
	v_max_u32_e32 v42, v41, v40
	v_cmp_ne_u32_e32 vcc, v28, v42
	v_bitop3_b32 v32, v42, 15, v42 bitop3:0xc
	v_lshlrev_b32_e64 v53, v32, 1
	v_cndmask_b32_e32 v43, 0, v28, vcc
	v_cmp_ne_u32_e32 vcc, v29, v42
	v_lshl_add_u64 v[32:33], v[174:175], 0, s[44:45]
	s_nop 0
	v_cndmask_b32_e32 v44, 0, v29, vcc
	v_cmp_ne_u32_e32 vcc, v30, v42
	s_nop 1
	v_cndmask_b32_e32 v45, 0, v30, vcc
	v_cmp_ne_u32_e32 vcc, v31, v42
	s_nop 1
	v_cndmask_b32_e32 v46, 0, v31, vcc
	v_cmp_ne_u32_e32 vcc, v24, v42
	s_nop 1
	v_cndmask_b32_e32 v47, 0, v24, vcc
	v_cmp_ne_u32_e32 vcc, v25, v42
	s_nop 1
	v_cndmask_b32_e32 v48, 0, v25, vcc
	v_cmp_ne_u32_e32 vcc, v26, v42
	v_lshlrev_b64 v[24:25], 8, v[36:37]
	v_lshl_add_u64 v[24:25], s[18:19], 0, v[24:25]
	v_cndmask_b32_e32 v49, 0, v26, vcc
	v_cmp_ne_u32_e32 vcc, v27, v42
	v_lshl_add_u64 v[28:29], v[24:25], 0, v[176:177]
	v_lshl_add_u64 v[36:37], v[32:33], 0, v[178:179]
	v_cndmask_b32_e32 v50, 0, v27, vcc
	v_cmp_ne_u32_e32 vcc, v38, v42
	global_load_dwordx4 v[24:27], v[28:29], off offset:16
	s_nop 0
	global_load_dwordx4 v[28:31], v[28:29], off
	v_cndmask_b32_e32 v51, 0, v38, vcc
	v_cmp_ne_u32_e32 vcc, v39, v42
	v_mov_b32_e32 v177, 0
	v_mov_b32_e32 v179, 0xff800000
	v_cndmask_b32_e32 v52, 0, v39, vcc
	global_load_dwordx4 v[32:35], v[36:37], off offset:16
	s_nop 0
	global_load_dwordx4 v[36:39], v[36:37], off
	v_cmp_ne_u32_e32 vcc, v20, v42
	s_waitcnt vmcnt(2)
	ds_write_b128 v208, v[28:31]
	ds_write_b128 v208, v[24:27] offset:16
	v_cndmask_b32_e32 v20, 0, v20, vcc
	v_cmp_ne_u32_e32 vcc, v2, v42
	s_waitcnt vmcnt(1)
	ds_write2_b64 v212, v[32:33], v[34:35] offset1:1
	v_cndmask_b32_e32 v2, 0, v2, vcc
	v_cmp_ne_u32_e32 vcc, v21, v42
	s_waitcnt vmcnt(0)
	ds_write2_b64 v211, v[36:37], v[38:39] offset1:1
	s_waitcnt lgkmcnt(0)
	v_cndmask_b32_e32 v21, 0, v21, vcc
	v_cmp_ne_u32_e32 vcc, v22, v42
	s_barrier
	s_nop 0
	v_cndmask_b32_e32 v22, 0, v22, vcc
	v_cmp_ne_u32_e32 vcc, v23, v42
	s_nop 1
	v_cndmask_b32_e32 v23, 0, v23, vcc
	v_cmp_lt_u32_e32 vcc, v40, v41
	v_max3_u32 v41, v43, v44, v45
	v_max3_u32 v41, v41, v46, v47
	v_max3_u32 v41, v41, v48, v49
	v_max3_u32 v41, v41, v50, v51
	v_max3_u32 v41, v41, v52, v20
	v_max3_u32 v41, v41, v2, v21
	v_cndmask_b32_e32 v40, 0, v40, vcc
	v_max3_u32 v41, v41, v22, v23
	v_max_u32_e32 v42, v41, v40
	v_bitop3_b32 v54, v42, 15, v42 bitop3:0xc
	v_lshlrev_b32_e64 v54, v54, 1
	v_cmp_ne_u32_e32 vcc, 0, v42
	s_nop 1
	v_cndmask_b32_e32 v54, 0, v54, vcc
	v_cmp_ne_u32_e32 vcc, v44, v42
	s_nop 1
	v_cndmask_b32_e32 v44, 0, v44, vcc
	v_max_u32_e32 v55, v43, v44
	v_cmp_eq_u32_e32 vcc, v43, v42
	s_nop 1
	v_cndmask_b32_e32 v43, v55, v44, vcc
	v_max_u32_e32 v44, v43, v45
	v_cmp_eq_u32_e32 vcc, v45, v42
	s_nop 1
	v_cndmask_b32_e32 v43, v44, v43, vcc
	v_max_u32_e32 v44, v43, v46
	v_cmp_eq_u32_e32 vcc, v46, v42
	s_nop 1
	v_cndmask_b32_e32 v43, v44, v43, vcc
	v_max_u32_e32 v44, v43, v47
	v_cmp_eq_u32_e32 vcc, v47, v42
	s_nop 1
	v_cndmask_b32_e32 v43, v44, v43, vcc
	v_max_u32_e32 v44, v43, v48
	v_cmp_eq_u32_e32 vcc, v48, v42
	s_nop 1
	v_cndmask_b32_e32 v43, v44, v43, vcc
	v_max_u32_e32 v44, v43, v49
	v_cmp_eq_u32_e32 vcc, v49, v42
	s_nop 1
	v_cndmask_b32_e32 v43, v44, v43, vcc
	v_max_u32_e32 v44, v43, v50
	v_cmp_eq_u32_e32 vcc, v50, v42
	s_nop 1
	v_cndmask_b32_e32 v43, v44, v43, vcc
	v_max_u32_e32 v44, v43, v51
	v_cmp_eq_u32_e32 vcc, v51, v42
	s_nop 1
	v_cndmask_b32_e32 v43, v44, v43, vcc
	v_max_u32_e32 v44, v43, v52
	v_cmp_eq_u32_e32 vcc, v52, v42
	s_nop 1
	v_cndmask_b32_e32 v43, v44, v43, vcc
	v_max_u32_e32 v44, v43, v20
	v_cmp_eq_u32_e32 vcc, v20, v42
	s_nop 1
	v_cndmask_b32_e32 v20, v44, v43, vcc
	v_max_u32_e32 v43, v20, v2
	v_cmp_eq_u32_e32 vcc, v2, v42
	s_nop 1
	v_cndmask_b32_e32 v2, v43, v20, vcc
	v_max_u32_e32 v20, v2, v21
	v_cmp_eq_u32_e32 vcc, v21, v42
	s_nop 1
	v_cndmask_b32_e32 v2, v20, v2, vcc
	v_max_u32_e32 v20, v2, v22
	v_cmp_eq_u32_e32 vcc, v22, v42
	s_nop 1
	v_cndmask_b32_e32 v2, v20, v2, vcc
	v_max_u32_e32 v20, v2, v23
	v_cmp_eq_u32_e32 vcc, v23, v42
	s_nop 1
	v_cndmask_b32_e32 v2, v20, v2, vcc
	v_max_u32_e32 v20, v2, v40
	v_cmp_lt_u32_e32 vcc, v40, v41
	v_mov_b64_e32 v[50:51], v[18:19]
	v_mov_b64_e32 v[48:49], v[16:17]
	v_cndmask_b32_e32 v2, v2, v20, vcc
	v_bitop3_b32 v20, v2, 15, v2 bitop3:0xc
	v_lshlrev_b32_e64 v20, v20, 1
	v_cmp_ne_u32_e32 vcc, 0, v2
	v_mov_b64_e32 v[46:47], v[14:15]
	v_mov_b64_e32 v[44:45], v[12:13]
	v_cndmask_b32_e32 v2, 0, v20, vcc
	v_or3_b32 v213, v54, v53, v2
	v_mov_b64_e32 v[34:35], v[18:19]
	v_mov_b64_e32 v[66:67], v[18:19]
	v_mov_b64_e32 v[32:33], v[16:17]
	v_mov_b64_e32 v[30:31], v[14:15]
	v_mov_b64_e32 v[28:29], v[12:13]
	v_mov_b64_e32 v[26:27], v[10:11]
	v_mov_b64_e32 v[24:25], v[8:9]
	v_mov_b64_e32 v[22:23], v[6:7]
	v_mov_b64_e32 v[20:21], v[4:5]
	v_mov_b64_e32 v[42:43], v[10:11]
	v_mov_b64_e32 v[40:41], v[8:9]
	v_mov_b64_e32 v[38:39], v[6:7]
	v_mov_b64_e32 v[36:37], v[4:5]
	v_mov_b64_e32 v[64:65], v[16:17]
	v_mov_b64_e32 v[62:63], v[14:15]
	v_mov_b64_e32 v[60:61], v[12:13]
	v_mov_b64_e32 v[58:59], v[10:11]
	v_mov_b64_e32 v[56:57], v[8:9]
	v_mov_b64_e32 v[54:55], v[6:7]
	v_mov_b64_e32 v[52:53], v[4:5]
